# v34 + phase-0 weight transpose loop processes two tiles per trip with both tiles' HBM loads in flight
# baseline (speedup 1.0000x reference)
.LBB0_14:
	s_mul_i32 s47, s47, s43
	s_sub_i32 s36, s45, s47
	s_ashr_i32 s43, s42, 31
	s_lshl_b32 s36, s36, 6
	s_lshl_b64 s[42:43], s[42:43], 2
	s_add_u32 s30, s30, s42
	s_addc_u32 s31, s31, s43
	v_or_b32_e32 v14, s36, v6
	s_ashr_i32 s37, s36, 31
	v_lshl_add_u64 v[18:19], s[30:31], 0, v[2:3]
	s_mul_i32 s42, s34, s37
	v_mul_lo_u32 v16, s35, v14
	v_mad_u64_u32 v[14:15], s[30:31], s34, v14, 0
	v_add_u32_e32 v20, s36, v8
	v_add3_u32 v15, v15, s42, v16
	v_ashrrev_i32_e32 v21, 31, v20
	v_lshl_add_u64 v[14:15], v[14:15], 2, v[18:19]
	v_mul_lo_u32 v22, s34, v21
	v_mul_lo_u32 v23, s35, v20
	v_mad_u64_u32 v[20:21], s[30:31], s34, v20, 0
	global_load_dwordx4 v[14:17], v[14:15], off
	v_add3_u32 v21, v21, v22, v23
	v_lshl_add_u64 v[18:19], v[20:21], 2, v[18:19]
	global_load_dwordx4 v[18:21], v[18:19], off
	v_add_u32_e32 v22, s46, v7
	v_ashrrev_i32_e32 v25, 31, v22
	v_mad_u64_u32 v[22:23], s[30:31], v22, s44, 0
	v_mov_b32_e32 v24, v23
	v_mad_u64_u32 v[24:25], s[30:31], v25, s44, v[24:25]
	v_mov_b32_e32 v23, v24
	v_lshl_add_u64 v[22:23], v[22:23], 1, s[28:29]
	s_add_i32 s41, s41, s72
	v_lshl_add_u64 v[22:23], s[36:37], 1, v[22:23]
	s_cmpk_gt_i32 s41, 0x2c1f
	v_lshl_add_u64 v[22:23], v[22:23], 0, v[4:5]
	s_cselect_b32 s98, 1, 0
	s_mov_b32 s99, 1
	s_cmp_lg_u32 s98, 0
	s_cbranch_scc1 .Lp0_procA_only
	s_branch .Lp0b_15
.Lp0_addrB:
	s_mul_i32 s47, s47, s43
	s_sub_i32 s36, s45, s47
	s_ashr_i32 s43, s42, 31
	s_lshl_b32 s36, s36, 6
	s_lshl_b64 s[42:43], s[42:43], 2
	s_add_u32 s30, s30, s42
	s_addc_u32 s31, s31, s43
	v_or_b32_e32 v26, s36, v6
	s_ashr_i32 s37, s36, 31
	v_lshl_add_u64 v[30:31], s[30:31], 0, v[2:3]
	s_mul_i32 s42, s34, s37
	v_mul_lo_u32 v28, s35, v26
	v_mad_u64_u32 v[26:27], s[30:31], s34, v26, 0
	v_add_u32_e32 v32, s36, v8
	v_add3_u32 v27, v27, s42, v28
	v_ashrrev_i32_e32 v33, 31, v32
	v_lshl_add_u64 v[26:27], v[26:27], 2, v[30:31]
	v_mul_lo_u32 v34, s34, v33
	v_mul_lo_u32 v35, s35, v32
	v_mad_u64_u32 v[32:33], s[30:31], s34, v32, 0
	global_load_dwordx4 v[26:29], v[26:27], off
	v_add3_u32 v33, v33, v34, v35
	v_lshl_add_u64 v[30:31], v[32:33], 2, v[30:31]
	global_load_dwordx4 v[30:33], v[30:31], off
	v_add_u32_e32 v34, s46, v7
	v_ashrrev_i32_e32 v37, 31, v34
	v_mad_u64_u32 v[34:35], s[30:31], v34, s44, 0
	v_mov_b32_e32 v36, v35
	v_mad_u64_u32 v[36:37], s[30:31], v37, s44, v[36:37]
	v_mov_b32_e32 v35, v36
	v_lshl_add_u64 v[34:35], v[34:35], 1, s[28:29]
	s_add_i32 s41, s41, s72
	v_lshl_add_u64 v[34:35], s[36:37], 1, v[34:35]
	s_cmpk_gt_i32 s41, 0x2c1f
	v_lshl_add_u64 v[34:35], v[34:35], 0, v[4:5]
	s_cselect_b32 s99, 1, 0
	s_waitcnt vmcnt(2)
	s_branch .Lp0_procA

.Lp0_procA:
	ds_write2_b32 v9, v14, v15 offset1:1
	ds_write2_b32 v9, v16, v17 offset0:2 offset1:3
	ds_write2_b32 v10, v18, v19 offset1:1
	ds_write2_b32 v11, v20, v21 offset1:1
	s_waitcnt lgkmcnt(0)
	s_barrier
	ds_read2_b32 v[14:15], v12 offset1:65
	ds_read2_b32 v[16:17], v12 offset0:130 offset1:195
	ds_read2_b32 v[18:19], v13 offset0:4 offset1:69
	ds_read2_b32 v[20:21], v13 offset0:134 offset1:199
	s_waitcnt lgkmcnt(3)
	v_cvt_pk_bf16_f32 v14, v14, v15
	s_waitcnt lgkmcnt(2)
	v_cvt_pk_bf16_f32 v15, v16, v17
	s_waitcnt lgkmcnt(1)
	v_cvt_pk_bf16_f32 v16, v18, v19
	s_waitcnt lgkmcnt(0)
	v_cvt_pk_bf16_f32 v17, v20, v21
	global_store_dwordx4 v[22:23], v[14:17], off
	s_barrier
	s_cmp_lg_u32 s98, 0
	s_cbranch_scc1 .LBB0_34
	s_waitcnt vmcnt(1)
	ds_write2_b32 v9, v26, v27 offset1:1
	ds_write2_b32 v9, v28, v29 offset0:2 offset1:3
	ds_write2_b32 v10, v30, v31 offset1:1
	ds_write2_b32 v11, v32, v33 offset1:1
	s_waitcnt lgkmcnt(0)
	s_barrier
	ds_read2_b32 v[26:27], v12 offset1:65
	ds_read2_b32 v[28:29], v12 offset0:130 offset1:195
	ds_read2_b32 v[30:31], v13 offset0:4 offset1:69
	ds_read2_b32 v[32:33], v13 offset0:134 offset1:199
	s_waitcnt lgkmcnt(3)
	v_cvt_pk_bf16_f32 v26, v26, v27
	s_waitcnt lgkmcnt(2)
	v_cvt_pk_bf16_f32 v27, v28, v29
	s_waitcnt lgkmcnt(1)
	v_cvt_pk_bf16_f32 v28, v30, v31
	s_waitcnt lgkmcnt(0)
	v_cvt_pk_bf16_f32 v29, v32, v33
	global_store_dwordx4 v[34:35], v[26:29], off
	s_barrier
	s_cmp_lg_u32 s99, 0
	s_cbranch_scc1 .LBB0_34

.LBB0_33:
	s_add_i32 s45, s41, 0xfffff3e0
	s_mov_b64 s[34:35], 0x2000
	s_movk_i32 s44, 0x800
	s_mov_b64 s[28:29], s[2:3]
	s_cbranch_execz .LBB0_24
	s_branch .LBB0_25
.Lp0b_15:
	s_cmpk_gt_i32 s41, 0x71f
	s_cselect_b64 s[36:37], -1, 0
	s_cmpk_lt_i32 s41, 0x720
	s_cbranch_scc1 .Lp0b_21
	s_cmpk_gt_u32 s41, 0x81f
	s_cbranch_scc0 .Lp0b_22
	s_cmpk_gt_u32 s41, 0xc1f
	s_cbranch_scc0 .Lp0b_23
	s_cmpk_gt_u32 s41, 0x1c1f
	s_cbranch_scc0 .Lp0b_32
	s_add_i32 s45, s41, 0xffffe3e0
	s_waitcnt lgkmcnt(0)
	s_mov_b64 s[30:31], s[60:61]
	s_cbranch_execz .Lp0b_33
	s_mov_b64 s[34:35], 0x800
	s_movk_i32 s44, 0x2000
	s_mov_b64 s[28:29], s[0:1]
	s_cbranch_execz .Lp0b_24
	s_branch .Lp0b_25

.Lp0b_27:
	s_lshr_b32 s43, s44, 6
	v_cvt_f32_u32_e32 v26, s43
	s_sub_i32 s47, 0, s43
	s_abs_i32 s46, s45
	s_ashr_i32 s42, s45, 31
	v_rcp_iflag_f32_e32 v26, v26
	s_nop 0
	v_mul_f32_e32 v26, 0x4f7ffffe, v26
	v_cvt_u32_f32_e32 v26, v26
	s_nop 0
	v_readfirstlane_b32 s68, v26
	s_mul_i32 s47, s47, s68
	s_mul_hi_u32 s47, s68, s47
	s_add_i32 s68, s68, s47
	s_mul_hi_u32 s47, s46, s68
	s_mul_i32 s68, s47, s43
	s_sub_i32 s46, s46, s68
	s_add_i32 s69, s47, 1
	s_sub_i32 s68, s46, s43
	s_cmp_ge_u32 s46, s43
	s_cselect_b32 s47, s69, s47
	s_cselect_b32 s46, s68, s46
	s_add_i32 s68, s47, 1
	s_cmp_ge_u32 s46, s43
	s_cselect_b32 s46, s68, s47
	s_xor_b32 s46, s46, s42
	s_sub_i32 s47, s46, s42
	s_lshl_b32 s42, s47, 6
	s_cmp_lt_i32 s47, 16
	s_cselect_b64 s[68:69], -1, 0
	s_or_b64 s[36:37], s[36:37], s[68:69]
	s_and_b64 vcc, exec, s[36:37]
	s_mov_b32 s46, s42
	s_cbranch_vccnz .Lp0_addrB
	s_cmpk_gt_u32 s42, 0x5ff
	s_mov_b64 s[36:37], -1
	s_cbranch_scc0 .Lp0b_30
	s_add_i32 s36, s42, 0xfffffe00
	s_cmpk_lt_u32 s42, 0xa00
	s_cselect_b32 s46, s36, s42
	s_mov_b64 s[36:37], 0
